# GEMM tile start: accumulator zeroing with 64 v_mov_b64 instead of 127 v_mov_b32 (6 tile-loop headers)
# speedup vs baseline: 1.0036x; 1.0035x over previous
.LBB0_343:
	s_ashr_i32 s11, s10, 31
	s_lshl_b64 s[16:17], s[10:11], 19
	s_add_u32 s16, s68, s16
	s_addc_u32 s17, s69, s17
	s_and_b64 s[18:19], s[0:1], exec
	s_cselect_b32 s11, s17, s25
	s_cselect_b32 s21, s16, s24
	s_ashr_i32 s9, s8, 31
	s_lshl_b64 s[18:19], s[8:9], 19
	s_add_u32 s18, s2, s18
	s_addc_u32 s19, s3, s19
	s_and_b64 s[28:29], s[0:1], exec
	s_cselect_b32 s9, s19, s27
	s_cselect_b32 s41, s18, s26
	s_add_u32 s24, s24, 0x40080
	s_addc_u32 s25, s25, 0
	s_add_u32 s42, s26, 0x100
	v_mov_b32_e32 v0, 0
	s_addc_u32 s43, s27, 0
	s_mov_b32 s44, -2
	v_mov_b64_e32 v[0:1], 0
	v_mov_b64_e32 v[2:3], 0
	v_mov_b64_e32 v[4:5], 0
	v_mov_b64_e32 v[6:7], 0
	v_mov_b64_e32 v[8:9], 0
	v_mov_b64_e32 v[10:11], 0
	v_mov_b64_e32 v[12:13], 0
	v_mov_b64_e32 v[14:15], 0
	v_mov_b64_e32 v[16:17], 0
	v_mov_b64_e32 v[18:19], 0
	v_mov_b64_e32 v[20:21], 0
	v_mov_b64_e32 v[22:23], 0
	v_mov_b64_e32 v[24:25], 0
	v_mov_b64_e32 v[26:27], 0
	v_mov_b64_e32 v[28:29], 0
	v_mov_b64_e32 v[30:31], 0
	v_mov_b64_e32 v[32:33], 0
	v_mov_b64_e32 v[34:35], 0
	v_mov_b64_e32 v[36:37], 0
	v_mov_b64_e32 v[38:39], 0
	v_mov_b64_e32 v[40:41], 0
	v_mov_b64_e32 v[42:43], 0
	v_mov_b64_e32 v[44:45], 0
	v_mov_b64_e32 v[46:47], 0
	v_mov_b64_e32 v[48:49], 0
	v_mov_b64_e32 v[50:51], 0
	v_mov_b64_e32 v[52:53], 0
	v_mov_b64_e32 v[54:55], 0
	v_mov_b64_e32 v[56:57], 0
	v_mov_b64_e32 v[58:59], 0
	v_mov_b64_e32 v[60:61], 0
	v_mov_b64_e32 v[62:63], 0
	v_mov_b64_e32 v[64:65], 0
	v_mov_b64_e32 v[66:67], 0
	v_mov_b64_e32 v[68:69], 0
	v_mov_b64_e32 v[70:71], 0
	v_mov_b64_e32 v[72:73], 0
	v_mov_b64_e32 v[74:75], 0
	v_mov_b64_e32 v[76:77], 0
	v_mov_b64_e32 v[78:79], 0
	v_mov_b64_e32 v[80:81], 0
	v_mov_b64_e32 v[82:83], 0
	v_mov_b64_e32 v[84:85], 0
	v_mov_b64_e32 v[86:87], 0
	v_mov_b64_e32 v[88:89], 0
	v_mov_b64_e32 v[90:91], 0
	v_mov_b64_e32 v[92:93], 0
	v_mov_b64_e32 v[94:95], 0
	v_mov_b64_e32 v[96:97], 0
	v_mov_b64_e32 v[98:99], 0
	v_mov_b64_e32 v[100:101], 0
	v_mov_b64_e32 v[102:103], 0
	v_mov_b64_e32 v[104:105], 0
	v_mov_b64_e32 v[106:107], 0
	v_mov_b64_e32 v[108:109], 0
	v_mov_b64_e32 v[110:111], 0
	v_mov_b64_e32 v[112:113], 0
	v_mov_b64_e32 v[114:115], 0
	v_mov_b64_e32 v[116:117], 0
	v_mov_b64_e32 v[118:119], 0
	v_mov_b64_e32 v[120:121], 0
	v_mov_b64_e32 v[122:123], 0
	v_mov_b64_e32 v[124:125], 0
	v_mov_b64_e32 v[126:127], 0

.LBB0_928:
	s_ashr_i32 s15, s14, 31
	s_lshl_b64 s[16:17], s[14:15], 19
	s_add_u32 s16, s88, s16
	s_addc_u32 s17, s89, s17
	s_and_b64 s[18:19], s[0:1], exec
	s_cselect_b32 s15, s17, s23
	s_cselect_b32 s39, s16, s22
	s_ashr_i32 s13, s12, 31
	s_lshl_b64 s[18:19], s[12:13], 19
	v_readlane_b32 s26, v254, 27
	v_readlane_b32 s27, v254, 28
	s_add_u32 s18, s26, s18
	s_addc_u32 s19, s27, s19
	s_and_b64 s[26:27], s[0:1], exec
	s_cselect_b32 s13, s19, s25
	s_cselect_b32 s40, s18, s24
	s_add_u32 s22, s22, 0x40080
	s_addc_u32 s23, s23, 0
	s_add_u32 s41, s24, 0x100
	v_mov_b32_e32 v0, 0
	s_addc_u32 s42, s25, 0
	s_mov_b32 s43, -2
	v_mov_b64_e32 v[0:1], 0
	v_mov_b64_e32 v[2:3], 0
	v_mov_b64_e32 v[4:5], 0
	v_mov_b64_e32 v[6:7], 0
	v_mov_b64_e32 v[8:9], 0
	v_mov_b64_e32 v[10:11], 0
	v_mov_b64_e32 v[12:13], 0
	v_mov_b64_e32 v[14:15], 0
	v_mov_b64_e32 v[16:17], 0
	v_mov_b64_e32 v[18:19], 0
	v_mov_b64_e32 v[20:21], 0
	v_mov_b64_e32 v[22:23], 0
	v_mov_b64_e32 v[24:25], 0
	v_mov_b64_e32 v[26:27], 0
	v_mov_b64_e32 v[28:29], 0
	v_mov_b64_e32 v[30:31], 0
	v_mov_b64_e32 v[32:33], 0
	v_mov_b64_e32 v[34:35], 0
	v_mov_b64_e32 v[36:37], 0
	v_mov_b64_e32 v[38:39], 0
	v_mov_b64_e32 v[40:41], 0
	v_mov_b64_e32 v[42:43], 0
	v_mov_b64_e32 v[44:45], 0
	v_mov_b64_e32 v[46:47], 0
	v_mov_b64_e32 v[48:49], 0
	v_mov_b64_e32 v[50:51], 0
	v_mov_b64_e32 v[52:53], 0
	v_mov_b64_e32 v[54:55], 0
	v_mov_b64_e32 v[56:57], 0
	v_mov_b64_e32 v[58:59], 0
	v_mov_b64_e32 v[60:61], 0
	v_mov_b64_e32 v[62:63], 0
	v_mov_b64_e32 v[64:65], 0
	v_mov_b64_e32 v[66:67], 0
	v_mov_b64_e32 v[68:69], 0
	v_mov_b64_e32 v[70:71], 0
	v_mov_b64_e32 v[72:73], 0
	v_mov_b64_e32 v[74:75], 0
	v_mov_b64_e32 v[76:77], 0
	v_mov_b64_e32 v[78:79], 0
	v_mov_b64_e32 v[80:81], 0
	v_mov_b64_e32 v[82:83], 0
	v_mov_b64_e32 v[84:85], 0
	v_mov_b64_e32 v[86:87], 0
	v_mov_b64_e32 v[88:89], 0
	v_mov_b64_e32 v[90:91], 0
	v_mov_b64_e32 v[92:93], 0
	v_mov_b64_e32 v[94:95], 0
	v_mov_b64_e32 v[96:97], 0
	v_mov_b64_e32 v[98:99], 0
	v_mov_b64_e32 v[100:101], 0
	v_mov_b64_e32 v[102:103], 0
	v_mov_b64_e32 v[104:105], 0
	v_mov_b64_e32 v[106:107], 0
	v_mov_b64_e32 v[108:109], 0
	v_mov_b64_e32 v[110:111], 0
	v_mov_b64_e32 v[112:113], 0
	v_mov_b64_e32 v[114:115], 0
	v_mov_b64_e32 v[116:117], 0
	v_mov_b64_e32 v[118:119], 0
	v_mov_b64_e32 v[120:121], 0
	v_mov_b64_e32 v[122:123], 0
	v_mov_b64_e32 v[124:125], 0
	v_mov_b64_e32 v[126:127], 0

.LBB0_1012:
	s_ashr_i32 s19, s18, 31
	s_lshl_b64 s[22:23], s[18:19], 19
	s_add_u32 s22, s88, s22
	s_addc_u32 s23, s89, s23
	s_and_b64 s[24:25], s[6:7], exec
	s_cselect_b32 s9, s23, s1
	s_cselect_b32 s19, s22, s0
	s_ashr_i32 s21, s20, 31
	s_lshl_b64 s[24:25], s[20:21], 19
	v_readlane_b32 s30, v254, 27
	v_readlane_b32 s31, v254, 28
	s_add_u32 s24, s30, s24
	s_addc_u32 s25, s31, s25
	s_and_b64 s[30:31], s[6:7], exec
	s_cselect_b32 s21, s25, s29
	s_cselect_b32 s27, s24, s28
	s_add_u32 s0, s0, 0x40080
	s_addc_u32 s1, s1, 0
	s_add_u32 s34, s28, 0x100
	v_mov_b32_e32 v0, 0
	s_addc_u32 s35, s29, 0
	s_mov_b32 s51, -2
	v_mov_b64_e32 v[0:1], 0
	v_mov_b64_e32 v[2:3], 0
	v_mov_b64_e32 v[4:5], 0
	v_mov_b64_e32 v[6:7], 0
	v_mov_b64_e32 v[8:9], 0
	v_mov_b64_e32 v[10:11], 0
	v_mov_b64_e32 v[12:13], 0
	v_mov_b64_e32 v[14:15], 0
	v_mov_b64_e32 v[16:17], 0
	v_mov_b64_e32 v[18:19], 0
	v_mov_b64_e32 v[20:21], 0
	v_mov_b64_e32 v[22:23], 0
	v_mov_b64_e32 v[24:25], 0
	v_mov_b64_e32 v[26:27], 0
	v_mov_b64_e32 v[28:29], 0
	v_mov_b64_e32 v[30:31], 0
	v_mov_b64_e32 v[32:33], 0
	v_mov_b64_e32 v[34:35], 0
	v_mov_b64_e32 v[36:37], 0
	v_mov_b64_e32 v[38:39], 0
	v_mov_b64_e32 v[40:41], 0
	v_mov_b64_e32 v[42:43], 0
	v_mov_b64_e32 v[44:45], 0
	v_mov_b64_e32 v[46:47], 0
	v_mov_b64_e32 v[48:49], 0
	v_mov_b64_e32 v[50:51], 0
	v_mov_b64_e32 v[52:53], 0
	v_mov_b64_e32 v[54:55], 0
	v_mov_b64_e32 v[56:57], 0
	v_mov_b64_e32 v[58:59], 0
	v_mov_b64_e32 v[60:61], 0
	v_mov_b64_e32 v[62:63], 0
	v_mov_b64_e32 v[64:65], 0
	v_mov_b64_e32 v[66:67], 0
	v_mov_b64_e32 v[68:69], 0
	v_mov_b64_e32 v[70:71], 0
	v_mov_b64_e32 v[72:73], 0
	v_mov_b64_e32 v[74:75], 0
	v_mov_b64_e32 v[76:77], 0
	v_mov_b64_e32 v[78:79], 0
	v_mov_b64_e32 v[80:81], 0
	v_mov_b64_e32 v[82:83], 0
	v_mov_b64_e32 v[84:85], 0
	v_mov_b64_e32 v[86:87], 0
	v_mov_b64_e32 v[88:89], 0
	v_mov_b64_e32 v[90:91], 0
	v_mov_b64_e32 v[92:93], 0
	v_mov_b64_e32 v[94:95], 0
	v_mov_b64_e32 v[96:97], 0
	v_mov_b64_e32 v[98:99], 0
	v_mov_b64_e32 v[100:101], 0
	v_mov_b64_e32 v[102:103], 0
	v_mov_b64_e32 v[104:105], 0
	v_mov_b64_e32 v[106:107], 0
	v_mov_b64_e32 v[108:109], 0
	v_mov_b64_e32 v[110:111], 0
	v_mov_b64_e32 v[112:113], 0
	v_mov_b64_e32 v[114:115], 0
	v_mov_b64_e32 v[116:117], 0
	v_mov_b64_e32 v[118:119], 0
	v_mov_b64_e32 v[120:121], 0
	v_mov_b64_e32 v[122:123], 0
	v_mov_b64_e32 v[124:125], 0
	v_mov_b64_e32 v[126:127], 0

.LBB0_1101:
	s_ashr_i32 s11, s10, 31
	s_lshl_b64 s[12:13], s[10:11], 19
	v_readlane_b32 s14, v255, 47
	v_readlane_b32 s15, v255, 48
	s_add_u32 s12, s14, s12
	s_addc_u32 s13, s15, s13
	s_and_b64 s[14:15], s[6:7], exec
	s_cselect_b32 s11, s13, s19
	s_cselect_b32 s38, s12, s18
	s_ashr_i32 s9, s8, 31
	s_lshl_b64 s[14:15], s[8:9], 19
	v_readlane_b32 s22, v254, 29
	v_readlane_b32 s23, v254, 30
	s_add_u32 s14, s22, s14
	s_addc_u32 s15, s23, s15
	s_and_b64 s[22:23], s[6:7], exec
	s_cselect_b32 s9, s15, s21
	s_cselect_b32 s39, s14, s20
	s_add_u32 s18, s18, 0x40080
	s_addc_u32 s19, s19, 0
	s_add_u32 s40, s20, 0x100
	v_mov_b32_e32 v0, 0
	s_addc_u32 s41, s21, 0
	s_mov_b32 s42, -2
	v_mov_b64_e32 v[0:1], 0
	v_mov_b64_e32 v[2:3], 0
	v_mov_b64_e32 v[4:5], 0
	v_mov_b64_e32 v[6:7], 0
	v_mov_b64_e32 v[8:9], 0
	v_mov_b64_e32 v[10:11], 0
	v_mov_b64_e32 v[12:13], 0
	v_mov_b64_e32 v[14:15], 0
	v_mov_b64_e32 v[16:17], 0
	v_mov_b64_e32 v[18:19], 0
	v_mov_b64_e32 v[20:21], 0
	v_mov_b64_e32 v[22:23], 0
	v_mov_b64_e32 v[24:25], 0
	v_mov_b64_e32 v[26:27], 0
	v_mov_b64_e32 v[28:29], 0
	v_mov_b64_e32 v[30:31], 0
	v_mov_b64_e32 v[32:33], 0
	v_mov_b64_e32 v[34:35], 0
	v_mov_b64_e32 v[36:37], 0
	v_mov_b64_e32 v[38:39], 0
	v_mov_b64_e32 v[40:41], 0
	v_mov_b64_e32 v[42:43], 0
	v_mov_b64_e32 v[44:45], 0
	v_mov_b64_e32 v[46:47], 0
	v_mov_b64_e32 v[48:49], 0
	v_mov_b64_e32 v[50:51], 0
	v_mov_b64_e32 v[52:53], 0
	v_mov_b64_e32 v[54:55], 0
	v_mov_b64_e32 v[56:57], 0
	v_mov_b64_e32 v[58:59], 0
	v_mov_b64_e32 v[60:61], 0
	v_mov_b64_e32 v[62:63], 0
	v_mov_b64_e32 v[64:65], 0
	v_mov_b64_e32 v[66:67], 0
	v_mov_b64_e32 v[68:69], 0
	v_mov_b64_e32 v[70:71], 0
	v_mov_b64_e32 v[72:73], 0
	v_mov_b64_e32 v[74:75], 0
	v_mov_b64_e32 v[76:77], 0
	v_mov_b64_e32 v[78:79], 0
	v_mov_b64_e32 v[80:81], 0
	v_mov_b64_e32 v[82:83], 0
	v_mov_b64_e32 v[84:85], 0
	v_mov_b64_e32 v[86:87], 0
	v_mov_b64_e32 v[88:89], 0
	v_mov_b64_e32 v[90:91], 0
	v_mov_b64_e32 v[92:93], 0
	v_mov_b64_e32 v[94:95], 0
	v_mov_b64_e32 v[96:97], 0
	v_mov_b64_e32 v[98:99], 0
	v_mov_b64_e32 v[100:101], 0
	v_mov_b64_e32 v[102:103], 0
	v_mov_b64_e32 v[104:105], 0
	v_mov_b64_e32 v[106:107], 0
	v_mov_b64_e32 v[108:109], 0
	v_mov_b64_e32 v[110:111], 0
	v_mov_b64_e32 v[112:113], 0
	v_mov_b64_e32 v[114:115], 0
	v_mov_b64_e32 v[116:117], 0
	v_mov_b64_e32 v[118:119], 0
	v_mov_b64_e32 v[120:121], 0
	v_mov_b64_e32 v[122:123], 0
	v_mov_b64_e32 v[124:125], 0
	v_mov_b64_e32 v[126:127], 0

.LBB0_1183:
	s_add_u32 s41, s20, 0x100
	v_mov_b32_e32 v0, 0
	s_addc_u32 s42, s21, 0
	s_mov_b32 s43, -2
	v_mov_b64_e32 v[0:1], 0
	v_mov_b64_e32 v[2:3], 0
	v_mov_b64_e32 v[4:5], 0
	v_mov_b64_e32 v[6:7], 0
	v_mov_b64_e32 v[8:9], 0
	v_mov_b64_e32 v[10:11], 0
	v_mov_b64_e32 v[12:13], 0
	v_mov_b64_e32 v[14:15], 0
	v_mov_b64_e32 v[16:17], 0
	v_mov_b64_e32 v[18:19], 0
	v_mov_b64_e32 v[20:21], 0
	v_mov_b64_e32 v[22:23], 0
	v_mov_b64_e32 v[24:25], 0
	v_mov_b64_e32 v[26:27], 0
	v_mov_b64_e32 v[28:29], 0
	v_mov_b64_e32 v[30:31], 0
	v_mov_b64_e32 v[32:33], 0
	v_mov_b64_e32 v[34:35], 0
	v_mov_b64_e32 v[36:37], 0
	v_mov_b64_e32 v[38:39], 0
	v_mov_b64_e32 v[40:41], 0
	v_mov_b64_e32 v[42:43], 0
	v_mov_b64_e32 v[44:45], 0
	v_mov_b64_e32 v[46:47], 0
	v_mov_b64_e32 v[48:49], 0
	v_mov_b64_e32 v[50:51], 0
	v_mov_b64_e32 v[52:53], 0
	v_mov_b64_e32 v[54:55], 0
	v_mov_b64_e32 v[56:57], 0
	v_mov_b64_e32 v[58:59], 0
	v_mov_b64_e32 v[60:61], 0
	v_mov_b64_e32 v[62:63], 0
	v_mov_b64_e32 v[64:65], 0
	v_mov_b64_e32 v[66:67], 0
	v_mov_b64_e32 v[68:69], 0
	v_mov_b64_e32 v[70:71], 0
	v_mov_b64_e32 v[72:73], 0
	v_mov_b64_e32 v[74:75], 0
	v_mov_b64_e32 v[76:77], 0
	v_mov_b64_e32 v[78:79], 0
	v_mov_b64_e32 v[80:81], 0
	v_mov_b64_e32 v[82:83], 0
	v_mov_b64_e32 v[84:85], 0
	v_mov_b64_e32 v[86:87], 0
	v_mov_b64_e32 v[88:89], 0
	v_mov_b64_e32 v[90:91], 0
	v_mov_b64_e32 v[92:93], 0
	v_mov_b64_e32 v[94:95], 0
	v_mov_b64_e32 v[96:97], 0
	v_mov_b64_e32 v[98:99], 0
	v_mov_b64_e32 v[100:101], 0
	v_mov_b64_e32 v[102:103], 0
	v_mov_b64_e32 v[104:105], 0
	v_mov_b64_e32 v[106:107], 0
	v_mov_b64_e32 v[108:109], 0
	v_mov_b64_e32 v[110:111], 0
	v_mov_b64_e32 v[112:113], 0
	v_mov_b64_e32 v[114:115], 0
	v_mov_b64_e32 v[116:117], 0
	v_mov_b64_e32 v[118:119], 0
	v_mov_b64_e32 v[120:121], 0
	v_mov_b64_e32 v[122:123], 0
	v_mov_b64_e32 v[124:125], 0
	v_mov_b64_e32 v[126:127], 0

.LBB0_1270:
	s_add_u32 s7, s34, 0x100
	v_mov_b32_e32 v0, 0
	s_addc_u32 s29, s35, 0
	s_mov_b32 s54, -2
	v_mov_b64_e32 v[0:1], 0
	v_mov_b64_e32 v[2:3], 0
	v_mov_b64_e32 v[4:5], 0
	v_mov_b64_e32 v[6:7], 0
	v_mov_b64_e32 v[8:9], 0
	v_mov_b64_e32 v[10:11], 0
	v_mov_b64_e32 v[12:13], 0
	v_mov_b64_e32 v[14:15], 0
	v_mov_b64_e32 v[16:17], 0
	v_mov_b64_e32 v[18:19], 0
	v_mov_b64_e32 v[20:21], 0
	v_mov_b64_e32 v[22:23], 0
	v_mov_b64_e32 v[24:25], 0
	v_mov_b64_e32 v[26:27], 0
	v_mov_b64_e32 v[28:29], 0
	v_mov_b64_e32 v[30:31], 0
	v_mov_b64_e32 v[32:33], 0
	v_mov_b64_e32 v[34:35], 0
	v_mov_b64_e32 v[36:37], 0
	v_mov_b64_e32 v[38:39], 0
	v_mov_b64_e32 v[40:41], 0
	v_mov_b64_e32 v[42:43], 0
	v_mov_b64_e32 v[44:45], 0
	v_mov_b64_e32 v[46:47], 0
	v_mov_b64_e32 v[48:49], 0
	v_mov_b64_e32 v[50:51], 0
	v_mov_b64_e32 v[52:53], 0
	v_mov_b64_e32 v[54:55], 0
	v_mov_b64_e32 v[56:57], 0
	v_mov_b64_e32 v[58:59], 0
	v_mov_b64_e32 v[60:61], 0
	v_mov_b64_e32 v[62:63], 0
	v_mov_b64_e32 v[64:65], 0
	v_mov_b64_e32 v[66:67], 0
	v_mov_b64_e32 v[68:69], 0
	v_mov_b64_e32 v[70:71], 0
	v_mov_b64_e32 v[72:73], 0
	v_mov_b64_e32 v[74:75], 0
	v_mov_b64_e32 v[76:77], 0
	v_mov_b64_e32 v[78:79], 0
	v_mov_b64_e32 v[80:81], 0
	v_mov_b64_e32 v[82:83], 0
	v_mov_b64_e32 v[84:85], 0
	v_mov_b64_e32 v[86:87], 0
	v_mov_b64_e32 v[88:89], 0
	v_mov_b64_e32 v[90:91], 0
	v_mov_b64_e32 v[92:93], 0
	v_mov_b64_e32 v[94:95], 0
	v_mov_b64_e32 v[96:97], 0
	v_mov_b64_e32 v[98:99], 0
	v_mov_b64_e32 v[100:101], 0
	v_mov_b64_e32 v[102:103], 0
	v_mov_b64_e32 v[104:105], 0
	v_mov_b64_e32 v[106:107], 0
	v_mov_b64_e32 v[108:109], 0
	v_mov_b64_e32 v[110:111], 0
	v_mov_b64_e32 v[112:113], 0
	v_mov_b64_e32 v[114:115], 0
	v_mov_b64_e32 v[116:117], 0
	v_mov_b64_e32 v[118:119], 0
	v_mov_b64_e32 v[120:121], 0
	v_mov_b64_e32 v[122:123], 0
	v_mov_b64_e32 v[124:125], 0
	v_mov_b64_e32 v[126:127], 0
